# correctness fix: the level-1 task's mid-group stores are write-through too (they are published by a counter, not by a barrier flush)
# baseline (speedup 1.0000x reference)
.LBB0_806:
	s_mov_b64 s[2:3], -1
	s_and_b64 vcc, exec, s[40:41]
	s_cbranch_vccz .LBB0_808
	s_and_b32 s2, s54, 0xffffffc0
	v_mul_u32_u24_e32 v66, 0x440, v186
	v_lshlrev_b32_e32 v67, 1, v185
	s_add_i32 s2, s2, 0
	v_add3_u32 v66, s2, v66, v67
	v_bfe_u32 v68, v18, 16, 1
	s_movk_i32 s2, 0x7fff
	v_add3_u32 v68, v18, v68, s2
	s_barrier
	ds_write_b16_d16_hi v66, v68 offset:49152
	v_bfe_u32 v68, v19, 16, 1
	v_add3_u32 v68, v19, v68, s2
	ds_write_b16_d16_hi v66, v68 offset:49424
	v_bfe_u32 v68, v20, 16, 1
	v_add3_u32 v68, v20, v68, s2
	ds_write_b16_d16_hi v66, v68 offset:49696
	v_bfe_u32 v68, v21, 16, 1
	v_add3_u32 v68, v21, v68, s2
	ds_write_b16_d16_hi v66, v68 offset:49968
	v_bfe_u32 v68, v22, 16, 1
	v_add3_u32 v68, v22, v68, s2
	ds_write_b16_d16_hi v66, v68 offset:51328
	v_bfe_u32 v68, v23, 16, 1
	v_add3_u32 v68, v23, v68, s2
	ds_write_b16_d16_hi v66, v68 offset:51600
	v_bfe_u32 v68, v24, 16, 1
	v_add3_u32 v68, v24, v68, s2
	ds_write_b16_d16_hi v66, v68 offset:51872
	v_bfe_u32 v68, v25, 16, 1
	v_add3_u32 v68, v25, v68, s2
	ds_write_b16_d16_hi v66, v68 offset:52144
	v_bfe_u32 v68, v26, 16, 1
	v_add3_u32 v68, v26, v68, s2
	ds_write_b16_d16_hi v66, v68 offset:53504
	v_bfe_u32 v68, v27, 16, 1
	v_add3_u32 v68, v27, v68, s2
	ds_write_b16_d16_hi v66, v68 offset:53776
	v_bfe_u32 v68, v28, 16, 1
	v_add3_u32 v68, v28, v68, s2
	ds_write_b16_d16_hi v66, v68 offset:54048
	v_bfe_u32 v68, v29, 16, 1
	v_add3_u32 v68, v29, v68, s2
	ds_write_b16_d16_hi v66, v68 offset:54320
	v_bfe_u32 v68, v30, 16, 1
	v_add3_u32 v68, v30, v68, s2
	ds_write_b16_d16_hi v66, v68 offset:55680
	v_bfe_u32 v68, v31, 16, 1
	v_add3_u32 v68, v31, v68, s2
	ds_write_b16_d16_hi v66, v68 offset:55952
	v_bfe_u32 v68, v32, 16, 1
	v_add3_u32 v68, v32, v68, s2
	ds_write_b16_d16_hi v66, v68 offset:56224
	v_bfe_u32 v68, v33, 16, 1
	v_add3_u32 v68, v33, v68, s2
	ds_write_b16_d16_hi v66, v68 offset:56496
	v_bfe_u32 v68, v34, 16, 1
	v_add3_u32 v68, v34, v68, s2
	ds_write_b16_d16_hi v66, v68 offset:57856
	v_bfe_u32 v68, v35, 16, 1
	v_add3_u32 v68, v35, v68, s2
	ds_write_b16_d16_hi v66, v68 offset:58128
	v_bfe_u32 v68, v36, 16, 1
	v_add3_u32 v68, v36, v68, s2
	ds_write_b16_d16_hi v66, v68 offset:58400
	v_bfe_u32 v68, v37, 16, 1
	v_add3_u32 v68, v37, v68, s2
	ds_write_b16_d16_hi v66, v68 offset:58672
	v_bfe_u32 v68, v38, 16, 1
	v_add3_u32 v68, v38, v68, s2
	ds_write_b16_d16_hi v66, v68 offset:60032
	v_bfe_u32 v68, v39, 16, 1
	v_add3_u32 v68, v39, v68, s2
	ds_write_b16_d16_hi v66, v68 offset:60304
	v_bfe_u32 v68, v40, 16, 1
	v_add3_u32 v68, v40, v68, s2
	ds_write_b16_d16_hi v66, v68 offset:60576
	v_bfe_u32 v68, v41, 16, 1
	v_add3_u32 v68, v41, v68, s2
	ds_write_b16_d16_hi v66, v68 offset:60848
	v_bfe_u32 v68, v42, 16, 1
	v_add3_u32 v68, v42, v68, s2
	ds_write_b16_d16_hi v66, v68 offset:62208
	v_bfe_u32 v68, v43, 16, 1
	v_add3_u32 v68, v43, v68, s2
	ds_write_b16_d16_hi v66, v68 offset:62480
	v_bfe_u32 v68, v44, 16, 1
	v_add3_u32 v68, v44, v68, s2
	ds_write_b16_d16_hi v66, v68 offset:62752
	v_bfe_u32 v68, v45, 16, 1
	v_add3_u32 v68, v45, v68, s2
	ds_write_b16_d16_hi v66, v68 offset:63024
	v_bfe_u32 v68, v46, 16, 1
	v_add3_u32 v68, v46, v68, s2
	ds_write_b16_d16_hi v66, v68 offset:64384
	v_bfe_u32 v68, v47, 16, 1
	v_add3_u32 v68, v47, v68, s2
	ds_write_b16_d16_hi v66, v68 offset:64656
	v_bfe_u32 v68, v48, 16, 1
	v_add3_u32 v68, v48, v68, s2
	ds_write_b16_d16_hi v66, v68 offset:64928
	v_bfe_u32 v68, v49, 16, 1
	v_add3_u32 v68, v49, v68, s2
	v_add_u32_e32 v67, 0xc000, v66
	ds_write_b16_d16_hi v66, v68 offset:65200
	v_bfe_u32 v66, v50, 16, 1
	v_add3_u32 v66, v50, v66, s2
	ds_write_b16_d16_hi v67, v66 offset:17408
	v_bfe_u32 v66, v51, 16, 1
	v_add3_u32 v66, v51, v66, s2
	ds_write_b16_d16_hi v67, v66 offset:17680
	v_bfe_u32 v66, v52, 16, 1
	v_add3_u32 v66, v52, v66, s2
	ds_write_b16_d16_hi v67, v66 offset:17952
	v_bfe_u32 v66, v53, 16, 1
	v_add3_u32 v66, v53, v66, s2
	ds_write_b16_d16_hi v67, v66 offset:18224
	v_bfe_u32 v66, v54, 16, 1
	v_add3_u32 v66, v54, v66, s2
	ds_write_b16_d16_hi v67, v66 offset:19584
	v_bfe_u32 v66, v55, 16, 1
	v_add3_u32 v66, v55, v66, s2
	ds_write_b16_d16_hi v67, v66 offset:19856
	v_bfe_u32 v66, v56, 16, 1
	v_add3_u32 v66, v56, v66, s2
	ds_write_b16_d16_hi v67, v66 offset:20128
	v_bfe_u32 v66, v57, 16, 1
	v_add3_u32 v66, v57, v66, s2
	ds_write_b16_d16_hi v67, v66 offset:20400
	v_bfe_u32 v66, v58, 16, 1
	v_add3_u32 v66, v58, v66, s2
	ds_write_b16_d16_hi v67, v66 offset:21760
	v_bfe_u32 v66, v59, 16, 1
	v_add3_u32 v66, v59, v66, s2
	ds_write_b16_d16_hi v67, v66 offset:22032
	v_bfe_u32 v66, v60, 16, 1
	v_add3_u32 v66, v60, v66, s2
	ds_write_b16_d16_hi v67, v66 offset:22304
	v_bfe_u32 v66, v61, 16, 1
	v_add3_u32 v66, v61, v66, s2
	ds_write_b16_d16_hi v67, v66 offset:22576
	v_bfe_u32 v66, v62, 16, 1
	v_add3_u32 v66, v62, v66, s2
	ds_write_b16_d16_hi v67, v66 offset:23936
	v_bfe_u32 v66, v63, 16, 1
	v_add3_u32 v66, v63, v66, s2
	ds_write_b16_d16_hi v67, v66 offset:24208
	v_bfe_u32 v66, v64, 16, 1
	v_add3_u32 v66, v64, v66, s2
	ds_write_b16_d16_hi v67, v66 offset:24480
	v_bfe_u32 v66, v65, 16, 1
	v_add3_u32 v66, v65, v66, s2
	ds_write_b16_d16_hi v67, v66 offset:24752
	v_bfe_u32 v66, v2, 16, 1
	v_add3_u32 v66, v2, v66, s2
	ds_write_b16_d16_hi v67, v66 offset:26112
	v_bfe_u32 v66, v3, 16, 1
	v_add3_u32 v66, v3, v66, s2
	ds_write_b16_d16_hi v67, v66 offset:26384
	v_bfe_u32 v66, v4, 16, 1
	v_add3_u32 v66, v4, v66, s2
	ds_write_b16_d16_hi v67, v66 offset:26656
	v_bfe_u32 v66, v5, 16, 1
	v_add3_u32 v66, v5, v66, s2
	ds_write_b16_d16_hi v67, v66 offset:26928
	v_bfe_u32 v66, v6, 16, 1
	v_add3_u32 v66, v6, v66, s2
	ds_write_b16_d16_hi v67, v66 offset:28288
	v_bfe_u32 v66, v7, 16, 1
	v_add3_u32 v66, v7, v66, s2
	ds_write_b16_d16_hi v67, v66 offset:28560
	v_bfe_u32 v66, v8, 16, 1
	v_add3_u32 v66, v8, v66, s2
	ds_write_b16_d16_hi v67, v66 offset:28832
	v_bfe_u32 v66, v9, 16, 1
	v_add3_u32 v66, v9, v66, s2
	ds_write_b16_d16_hi v67, v66 offset:29104
	v_bfe_u32 v66, v10, 16, 1
	v_add3_u32 v66, v10, v66, s2
	ds_write_b16_d16_hi v67, v66 offset:30464
	v_bfe_u32 v66, v11, 16, 1
	v_add3_u32 v66, v11, v66, s2
	ds_write_b16_d16_hi v67, v66 offset:30736
	v_bfe_u32 v66, v12, 16, 1
	v_add3_u32 v66, v12, v66, s2
	ds_write_b16_d16_hi v67, v66 offset:31008
	v_bfe_u32 v66, v13, 16, 1
	v_add3_u32 v66, v13, v66, s2
	ds_write_b16_d16_hi v67, v66 offset:31280
	v_bfe_u32 v66, v14, 16, 1
	v_add3_u32 v66, v14, v66, s2
	ds_write_b16_d16_hi v67, v66 offset:32640
	v_bfe_u32 v66, v15, 16, 1
	v_add3_u32 v66, v15, v66, s2
	ds_write_b16_d16_hi v67, v66 offset:32912
	v_bfe_u32 v66, v16, 16, 1
	v_add3_u32 v66, v16, v66, s2
	ds_write_b16_d16_hi v67, v66 offset:33184
	v_bfe_u32 v66, v17, 16, 1
	v_add3_u32 v66, v17, v66, s2
	v_readlane_b32 s3, v254, 27
	ds_write_b16_d16_hi v67, v66 offset:33456
	s_movk_i32 s2, 0x110
	v_lshl_or_b32 v66, s3, 5, v185
	v_mul_lo_u32 v66, v66, s2
	v_lshlrev_b32_e32 v67, 3, v186
	s_waitcnt lgkmcnt(0)
	v_add3_u32 v66, 0, v66, v67
	s_barrier
	v_add_u32_e32 v82, 0xc000, v66
	v_lshl_or_b32 v74, s3, 13, v178
	ds_read2_b64 v[66:69], v82 offset1:2
	ds_read2_b64 v[70:73], v82 offset0:4 offset1:6
	v_ashrrev_i32_e32 v75, 31, v74
	v_lshl_add_u64 v[78:79], s[42:43], 0, v[74:75]
	s_mov_b64 s[2:3], 0x8000
	v_lshl_add_u64 v[86:87], v[78:79], 0, s[2:3]
	s_mov_b32 s2, 0x9000
	ds_read2_b64 v[74:77], v82 offset0:8 offset1:10
	v_add_co_u32_e32 v88, vcc, s2, v78
	s_mov_b64 s[2:3], 0
	s_nop 0
	v_addc_co_u32_e32 v89, vcc, 0, v79, vcc
	s_waitcnt lgkmcnt(2)
	global_store_dwordx4 v[88:89], v[66:69], off offset:-4096 sc1
	s_waitcnt lgkmcnt(1)
	global_store_dwordx4 v[86:87], v[70:73], off offset:1024 sc1
	s_waitcnt lgkmcnt(0)
	global_store_dwordx4 v[86:87], v[74:77], off offset:2048 sc1
	ds_read2_b64 v[66:69], v82 offset0:12 offset1:14
	ds_read2_b64 v[70:73], v82 offset0:16 offset1:18
	ds_read2_b64 v[74:77], v82 offset0:20 offset1:22
	ds_read2_b64 v[78:81], v82 offset0:24 offset1:26
	ds_read2_b64 v[82:85], v82 offset0:28 offset1:30
	s_waitcnt lgkmcnt(4)
	global_store_dwordx4 v[86:87], v[66:69], off offset:3072 sc1
	s_waitcnt lgkmcnt(3)
	global_store_dwordx4 v[88:89], v[70:73], off sc1
	s_waitcnt lgkmcnt(2)
	global_store_dwordx4 v[88:89], v[74:77], off offset:1024 sc1
	s_waitcnt lgkmcnt(1)
	global_store_dwordx4 v[88:89], v[78:81], off offset:2048 sc1
	s_waitcnt lgkmcnt(0)
	global_store_dwordx4 v[88:89], v[82:85], off offset:3072 sc1
	s_waitcnt lgkmcnt(0)
	s_barrier
.LBB0_808:
	s_andn2_b64 vcc, exec, s[2:3]
	s_cbranch_vccnz .LBB0_810
	v_readlane_b32 s2, v254, 27
	s_lshl_b32 s2, s2, 13
	v_mov_b32_e32 v181, 0
	v_lshl_add_u64 v[66:67], s[42:43], 0, v[180:181]
	s_ashr_i32 s3, s2, 31
	v_lshl_add_u64 v[74:75], v[66:67], 0, s[2:3]
	v_cvt_pk_bf16_f32 v66, v18, v19
	v_cvt_pk_bf16_f32 v67, v20, v21
	v_cvt_pk_bf16_f32 v68, v22, v23
	v_cvt_pk_bf16_f32 v69, v24, v25
	v_cvt_pk_bf16_f32 v70, v26, v27
	v_cvt_pk_bf16_f32 v71, v28, v29
	v_cvt_pk_bf16_f32 v72, v30, v31
	v_cvt_pk_bf16_f32 v73, v32, v33
	global_store_dwordx4 v[74:75], v[66:69], off sc1
	global_store_dwordx4 v[74:75], v[70:73], off offset:16 sc1
	s_movk_i32 s2, 0x1000
	v_cvt_pk_bf16_f32 v66, v34, v35
	v_cvt_pk_bf16_f32 v67, v36, v37
	v_cvt_pk_bf16_f32 v68, v38, v39
	v_cvt_pk_bf16_f32 v69, v40, v41
	v_cvt_pk_bf16_f32 v70, v42, v43
	v_cvt_pk_bf16_f32 v71, v44, v45
	v_cvt_pk_bf16_f32 v72, v46, v47
	v_cvt_pk_bf16_f32 v73, v48, v49
	global_store_dwordx4 v[74:75], v[66:69], off offset:2048 sc1
	global_store_dwordx4 v[74:75], v[70:73], off offset:2064 sc1
	v_add_co_u32_e32 v74, vcc, s2, v74
	v_cvt_pk_bf16_f32 v66, v50, v51
	v_cvt_pk_bf16_f32 v67, v52, v53
	v_cvt_pk_bf16_f32 v68, v54, v55
	v_cvt_pk_bf16_f32 v69, v56, v57
	v_addc_co_u32_e32 v75, vcc, 0, v75, vcc
	v_cvt_pk_bf16_f32 v70, v58, v59
	v_cvt_pk_bf16_f32 v71, v60, v61
	v_cvt_pk_bf16_f32 v72, v62, v63
	v_cvt_pk_bf16_f32 v73, v64, v65
	global_store_dwordx4 v[74:75], v[66:69], off sc1
	global_store_dwordx4 v[74:75], v[70:73], off offset:16 sc1
	s_nop 0
	v_cvt_pk_bf16_f32 v66, v2, v3
	v_cvt_pk_bf16_f32 v67, v4, v5
	v_cvt_pk_bf16_f32 v68, v6, v7
	v_cvt_pk_bf16_f32 v69, v8, v9
	v_cvt_pk_bf16_f32 v70, v10, v11
	v_cvt_pk_bf16_f32 v71, v12, v13
	v_cvt_pk_bf16_f32 v72, v14, v15
	v_cvt_pk_bf16_f32 v73, v16, v17
	global_store_dwordx4 v[74:75], v[66:69], off offset:2048 sc1
	global_store_dwordx4 v[74:75], v[70:73], off offset:2064 sc1
